# v34 + the scan's per-unit prefetch block also touches eight rows of the o|z projection columns (P5's cold input), rows = ticket*8..
# speedup vs baseline: 1.0125x; 1.0125x over previous
.Lpf_a:
	v_readfirstlane_b32 s26, v184
	s_cmp_lt_u32 s26, 64
	s_cbranch_scc0 .Lpf_a_end
	v_readfirstlane_b32 s27, v255
	s_cmp_ge_u32 s27, 0x400
	s_cbranch_scc1 .Lpf_a_end
	s_mov_b32 s101, s27
	s_and_b32 s58, s27, 0x1ff
	s_lshr_b32 s59, s58, 4
	s_lshl_b32 s59, s59, 7
	s_cmp_lt_u32 s27, 0x200
	s_cbranch_scc0 .Lpf_a_ssd
	s_mul_i32 s60, s59, 0x3000
	s_bfe_u32 s61, s58, 0x20002
	s_lshl_b32 s61, s61, 8
	s_and_b32 s72, s58, 3
	s_lshl_b32 s72, s72, 7
	s_lshl_b32 s73, s61, 1
	s_add_u32 s72, s72, s73
	s_add_u32 s72, s72, 0x800
	s_add_u32 s73, s61, 0x400
	s_movk_i32 s98, 0x3000
	s_mov_b32 s99, 0x8500000
	s_branch .Lpf_a_go

.Lpf_a_go:
	s_add_u32 s26, s28, s99
	s_addc_u32 s27, s29, 0
	s_add_u32 s26, s26, s60
	s_addc_u32 s27, s27, 0
	v_mbcnt_hi_u32_b32 v46, -1, v185
	v_lshrrev_b32_e32 v45, 1, v46
	v_and_b32_e32 v47, 1, v46
	v_mul_lo_u32 v45, v45, s98
	v_mul_lo_u32 v46, v46, s98
	v_lshl_add_u32 v45, v47, 7, v45
	s_lshl_b32 s100, s98, 5
	s_add_u32 s58, s26, s61
	s_addc_u32 s59, s27, 0
	global_load_dword v44, v45, s[58:59]
	s_add_u32 s58, s58, s100
	s_addc_u32 s59, s59, 0
	global_load_dword v44, v45, s[58:59]
	s_add_u32 s58, s58, s100
	s_addc_u32 s59, s59, 0
	global_load_dword v44, v45, s[58:59]
	s_add_u32 s58, s58, s100
	s_addc_u32 s59, s59, 0
	global_load_dword v44, v45, s[58:59]
	s_add_u32 s58, s26, s73
	s_addc_u32 s59, s27, 0
	global_load_dword v44, v45, s[58:59]
	s_add_u32 s58, s58, s100
	s_addc_u32 s59, s59, 0
	global_load_dword v44, v45, s[58:59]
	s_add_u32 s58, s58, s100
	s_addc_u32 s59, s59, 0
	global_load_dword v44, v45, s[58:59]
	s_add_u32 s58, s58, s100
	s_addc_u32 s59, s59, 0
	global_load_dword v44, v45, s[58:59]
	s_add_u32 s58, s26, s72
	s_addc_u32 s59, s27, 0
	global_load_dword v44, v46, s[58:59]
	s_lshl_b32 s100, s100, 1
	s_add_u32 s58, s58, s100
	s_addc_u32 s59, s59, 0
	global_load_dword v44, v46, s[58:59]
	s_mul_i32 s58, s101, 0x18000
	s_add_u32 s26, s28, 0x8501000
	s_addc_u32 s27, s29, 0
	s_add_u32 s26, s26, s58
	s_addc_u32 s27, s27, 0
	v_mbcnt_hi_u32_b32 v47, -1, v185
	v_lshlrev_b32_e32 v47, 6, v47
	global_load_dword v44, v47, s[26:27]
	s_add_u32 s26, s26, 0x3000
	s_addc_u32 s27, s27, 0
	global_load_dword v44, v47, s[26:27]
	s_add_u32 s26, s26, 0x3000
	s_addc_u32 s27, s27, 0
	global_load_dword v44, v47, s[26:27]
	s_add_u32 s26, s26, 0x3000
	s_addc_u32 s27, s27, 0
	global_load_dword v44, v47, s[26:27]
	s_add_u32 s26, s26, 0x3000
	s_addc_u32 s27, s27, 0
	global_load_dword v44, v47, s[26:27]
	s_add_u32 s26, s26, 0x3000
	s_addc_u32 s27, s27, 0
	global_load_dword v44, v47, s[26:27]
	s_add_u32 s26, s26, 0x3000
	s_addc_u32 s27, s27, 0
	global_load_dword v44, v47, s[26:27]
	s_add_u32 s26, s26, 0x3000
	s_addc_u32 s27, s27, 0
	global_load_dword v44, v47, s[26:27]

.Lpf_b_end:
	s_branch .LBB0_631
	s_nop 0
	s_nop 0
	s_nop 0
	s_nop 0
	s_nop 0
	s_nop 0
	s_nop 0
	s_nop 0
	s_nop 0
	s_nop 0
	s_nop 0
	s_nop 0
	s_nop 0
	s_nop 0
	s_nop 0
	s_nop 0
	s_nop 0
	s_nop 0
	s_nop 0
	s_nop 0
	s_nop 0
	s_nop 0
	s_nop 0
	s_nop 0
	s_nop 0
	s_nop 0
	s_nop 0
	s_nop 0
	s_nop 0
	s_nop 0
	s_nop 0
	s_nop 0
	s_nop 0
	s_nop 0
	s_nop 0
	s_nop 0
	s_nop 0
	s_nop 0
	s_nop 0
	s_nop 0
	s_nop 0
	s_nop 0
	s_nop 0
	s_nop 0
	s_nop 0
	s_nop 0
	s_nop 0
	s_nop 0
	s_nop 0
	s_nop 0
	s_nop 0
	s_nop 0
	s_nop 0
	s_nop 0
	s_nop 0
	s_nop 0
	s_nop 0
	s_nop 0
	s_nop 0
	s_nop 0
	s_nop 0
	s_nop 0
	s_nop 0
	s_nop 0
	s_nop 0
	s_nop 0
	s_nop 0
	s_nop 0
	s_nop 0
	s_nop 0
	s_nop 0
	s_nop 0
	s_nop 0
	s_nop 0
	s_nop 0
	s_nop 0
	s_nop 0
	s_nop 0
	s_nop 0
	s_nop 0
	s_nop 0
	s_nop 0
	s_nop 0
	s_nop 0
	s_nop 0
	s_nop 0
	s_nop 0
	s_nop 0
	s_nop 0
	s_nop 0
	s_nop 0
	s_nop 0
	s_nop 0
	s_nop 0
	s_nop 0
	s_nop 0
	s_nop 0
	s_nop 0
	s_nop 0
	s_nop 0
	s_nop 0
	s_nop 0
	s_nop 0
	s_nop 0
	s_nop 0
	s_nop 0
	s_nop 0
	s_nop 0
	s_nop 0
	s_nop 0
	s_nop 0
	s_nop 0
	s_nop 0
	s_nop 0
	s_nop 0
	s_nop 0
	s_nop 0
	s_nop 0
	s_nop 0
	s_nop 0
	s_nop 0
	s_nop 0
	s_nop 0
	s_nop 0
	s_nop 0
	s_nop 0
	s_nop 0
	s_nop 0
	s_nop 0
	s_nop 0
	s_nop 0
	s_nop 0
	s_nop 0
	s_nop 0
	s_nop 0
	s_nop 0
	s_nop 0
	s_nop 0
	s_nop 0
	s_nop 0
	s_nop 0
	s_nop 0
	s_nop 0
	s_nop 0
	s_nop 0
	s_nop 0
	s_nop 0
	s_nop 0
	s_nop 0
	s_nop 0
	s_nop 0
	s_nop 0
	s_nop 0
	s_nop 0
	s_nop 0
	s_nop 0
	s_nop 0
	s_nop 0
	s_nop 0
	s_nop 0
	s_nop 0
	s_nop 0
	s_nop 0
	s_nop 0
	s_nop 0
	s_nop 0
	s_nop 0
	s_nop 0
	s_nop 0
	s_nop 0
	s_nop 0
	s_nop 0
	s_nop 0
	s_nop 0
	s_nop 0
	s_nop 0
	s_nop 0
	s_nop 0
	s_nop 0
	s_nop 0
	s_nop 0
	s_nop 0
	s_nop 0
	s_nop 0
	s_nop 0
	s_nop 0
	s_nop 0
	s_nop 0
	s_nop 0
	s_nop 0
	s_nop 0
	s_nop 0
	s_nop 0
	s_nop 0
	s_nop 0
	s_nop 0
	s_nop 0
	s_nop 0
	s_nop 0
	s_nop 0
	s_nop 0
	s_nop 0
	s_nop 0
	s_nop 0
	s_nop 0
	s_nop 0
	s_nop 0
	s_nop 0
	s_nop 0
	s_nop 0
	s_nop 0
	s_nop 0
	s_nop 0
	s_nop 0
	s_nop 0
	s_nop 0
	s_nop 0
	s_nop 0
	s_nop 0
	s_nop 0
	s_nop 0
	s_nop 0
	s_nop 0
	s_nop 0
	s_nop 0
	s_nop 0
	s_nop 0
	s_nop 0
	s_nop 0
	s_nop 0
	s_nop 0
	s_nop 0
	s_nop 0
	s_nop 0
	s_nop 0
	s_nop 0
	s_nop 0
	s_nop 0
	s_nop 0
	s_nop 0
	s_nop 0
	s_nop 0
	s_nop 0
	s_nop 0
	s_nop 0
	s_nop 0
	s_nop 0
	s_nop 0
	s_nop 0
	s_nop 0
	s_nop 0
	s_nop 0
	s_nop 0
	s_nop 0
	s_nop 0
	s_nop 0
	s_nop 0
	s_nop 0
	s_nop 0
	s_nop 0
	s_nop 0
	s_nop 0
	s_nop 0
	s_nop 0
	s_nop 0
	s_nop 0
	s_nop 0
	s_nop 0
	s_nop 0
	s_nop 0
	s_nop 0
	s_nop 0
	s_nop 0
	s_nop 0
	s_nop 0
	s_nop 0
	s_nop 0
	s_nop 0
	s_nop 0
	s_nop 0
	s_nop 0
	s_nop 0
	s_nop 0
	s_nop 0
	s_nop 0
	s_nop 0
	s_nop 0
	s_nop 0
	s_nop 0
	s_nop 0
	s_nop 0
	s_nop 0
	s_nop 0
	s_nop 0
	s_nop 0
	s_nop 0
	s_nop 0
	s_nop 0
	s_nop 0
	s_nop 0
	s_nop 0
	s_nop 0
	s_nop 0
	s_nop 0
	s_nop 0
	s_nop 0
	s_nop 0
	s_nop 0
	s_nop 0
	s_nop 0
	s_nop 0
	s_nop 0
	s_nop 0
	s_nop 0
	s_nop 0
	s_nop 0
	s_nop 0
	s_nop 0
	s_nop 0
	s_nop 0
	s_nop 0
	s_nop 0
	s_nop 0
	s_nop 0
	s_nop 0
	s_nop 0
	s_nop 0
	s_nop 0
	s_nop 0
	s_nop 0
	s_nop 0
	s_nop 0
	s_nop 0
	s_nop 0
	s_nop 0
	s_nop 0
	s_nop 0
	s_nop 0
	s_nop 0
	s_nop 0
	s_nop 0
	s_nop 0
	s_nop 0
	s_nop 0
	s_nop 0
	s_nop 0
	s_nop 0
	s_nop 0
	s_nop 0
	s_nop 0
	s_nop 0
	s_nop 0
	s_nop 0
	s_nop 0
	s_nop 0
	s_nop 0
	s_nop 0
	s_nop 0
	s_nop 0
	s_nop 0
	s_nop 0
	s_nop 0
	s_nop 0
	s_nop 0
	s_nop 0
	s_nop 0
	s_nop 0
	s_nop 0
	s_nop 0
	s_nop 0
	s_nop 0
	s_nop 0
	s_nop 0
	s_nop 0
	s_nop 0
	s_nop 0
	s_nop 0
	s_nop 0
	s_nop 0
	s_nop 0
	s_nop 0
	s_nop 0
	s_nop 0
	s_nop 0
	s_nop 0
	s_nop 0
	s_nop 0
	s_nop 0
	s_nop 0
	s_nop 0
	s_nop 0
	s_nop 0
	s_nop 0
	s_nop 0
	s_nop 0
	s_nop 0
	s_nop 0
	s_nop 0
	s_nop 0
	s_nop 0
	s_nop 0
	s_nop 0
	s_nop 0
	s_nop 0
	s_nop 0
	s_nop 0
	s_nop 0
	s_nop 0
	s_nop 0
	s_nop 0
	s_nop 0
	s_nop 0
	s_nop 0
	s_nop 0
	s_nop 0
	s_nop 0
	s_nop 0
	s_nop 0
	s_nop 0
	s_nop 0
	s_nop 0
	s_nop 0
	s_nop 0
	s_nop 0
	s_nop 0
	s_nop 0
	s_nop 0
	s_nop 0
	s_nop 0
	s_nop 0
	s_nop 0
	s_nop 0
	s_nop 0
	s_nop 0
	s_nop 0
	s_nop 0
	s_nop 0
	s_nop 0
	s_nop 0
	s_nop 0
	s_nop 0
	s_nop 0
	s_nop 0
	s_nop 0
	s_nop 0
	s_nop 0
	s_nop 0
	s_nop 0
	s_nop 0
	s_nop 0
	s_nop 0
	s_nop 0
	s_nop 0
	s_nop 0
	s_nop 0
	s_nop 0
	s_nop 0
	s_nop 0
	s_nop 0
	s_nop 0
	s_nop 0
	s_nop 0
	s_nop 0
	s_nop 0
	s_nop 0
	s_nop 0
	s_nop 0
	s_nop 0
	s_nop 0
	s_nop 0
	s_nop 0
	s_nop 0
	s_nop 0
	s_nop 0
	s_nop 0
	s_nop 0
	s_nop 0
	s_nop 0
	s_nop 0
	s_nop 0
	s_nop 0
	s_nop 0
	s_nop 0
	s_nop 0
	s_nop 0
	s_nop 0
	s_nop 0
	s_nop 0
	s_nop 0
	s_nop 0
	s_nop 0
	s_nop 0
	s_nop 0
	s_nop 0
	s_nop 0
	s_nop 0
	s_nop 0
	s_nop 0
	s_nop 0
	s_nop 0
	s_nop 0
	s_nop 0
	s_nop 0
	s_nop 0
	s_nop 0
	s_nop 0
	s_nop 0
	s_nop 0
	s_nop 0
	s_nop 0
	s_nop 0
	s_nop 0
	s_nop 0
	s_nop 0
	s_nop 0
	s_nop 0
	s_nop 0
	s_nop 0
	s_nop 0
	s_nop 0
	s_nop 0
	s_nop 0
	s_nop 0
	s_nop 0
	s_nop 0
	s_nop 0
	s_nop 0
	s_nop 0
	s_nop 0
	s_nop 0
	s_nop 0
	s_nop 0
	s_nop 0
	s_nop 0
	s_nop 0
	s_nop 0
	s_nop 0
	s_nop 0
	s_nop 0
	s_nop 0
	s_nop 0
	s_nop 0
	s_nop 0
	s_nop 0
	s_nop 0
	s_nop 0
	s_nop 0
	s_nop 0
	s_nop 0
	s_nop 0
	s_nop 0
	s_nop 0
	s_nop 0
	s_nop 0
	s_nop 0
	s_nop 0
	s_nop 0
	s_nop 0
	s_nop 0
	s_nop 0
	s_nop 0
	s_nop 0
	s_nop 0
	s_nop 0
	s_nop 0
	s_nop 0
	s_nop 0
	s_nop 0
	s_nop 0
	s_nop 0
	s_nop 0
	s_nop 0
	s_nop 0
	s_nop 0
	s_nop 0
	s_nop 0
	s_nop 0
	s_nop 0
	s_nop 0
	s_nop 0
	s_nop 0
	s_nop 0
	s_nop 0
	s_nop 0
	s_nop 0
	s_nop 0
	s_nop 0
	s_nop 0
	s_nop 0
	s_nop 0
	s_nop 0
	s_nop 0
	s_nop 0
	s_nop 0
	s_nop 0
	s_nop 0
	s_nop 0
	s_nop 0
	s_nop 0
	s_nop 0
	s_nop 0
	s_nop 0
	s_nop 0
	s_nop 0
	s_nop 0
	s_nop 0
	s_nop 0
	s_nop 0
	s_nop 0
	s_nop 0
	s_nop 0
	s_nop 0
	s_nop 0
	s_nop 0
	s_nop 0
	s_nop 0
	s_nop 0
	s_nop 0
	s_nop 0
	s_nop 0
	s_nop 0
	s_nop 0
	s_nop 0
	s_nop 0
	s_nop 0
	s_nop 0
	s_nop 0
	s_nop 0
	s_nop 0
	s_nop 0
	s_nop 0
	s_nop 0
	s_nop 0
	s_nop 0
	s_nop 0
	s_nop 0
	s_nop 0
	s_nop 0
	s_nop 0
	s_nop 0
	s_nop 0
	s_nop 0
	s_nop 0
	s_nop 0
	s_nop 0
	s_nop 0
	s_nop 0
	s_nop 0
	s_nop 0
	s_nop 0
	s_nop 0
	s_nop 0
	s_nop 0
	s_nop 0
	s_nop 0
	s_nop 0
	s_nop 0
	s_nop 0
	s_nop 0
	s_nop 0
	s_nop 0
	s_nop 0
	s_nop 0
	s_nop 0
	s_nop 0
	s_nop 0
	s_nop 0
	s_nop 0
	s_nop 0
	s_nop 0
	s_nop 0
	s_nop 0
	s_nop 0
	s_nop 0
	s_nop 0
	s_nop 0
	s_nop 0
	s_nop 0
	s_nop 0
	s_nop 0
	s_nop 0
	s_nop 0
	s_nop 0
	s_nop 0
	s_nop 0
	s_nop 0
	s_nop 0
	s_nop 0
	s_nop 0
	s_nop 0
	s_nop 0
	s_nop 0
	s_nop 0
	s_nop 0
	s_nop 0
	s_nop 0
	s_nop 0
	s_nop 0
	s_nop 0
	s_nop 0
	s_nop 0
	s_nop 0
	s_nop 0
	s_nop 0
	s_nop 0
	s_nop 0
	s_nop 0
	s_nop 0
	s_nop 0
	s_nop 0
	s_nop 0
	s_nop 0
	s_nop 0
	s_nop 0
	s_nop 0
	s_nop 0
	s_nop 0
	s_nop 0
	s_nop 0
	s_nop 0
	s_nop 0
	s_nop 0
	s_nop 0
	s_nop 0
	s_nop 0
	s_nop 0
	s_nop 0
	s_nop 0
	s_nop 0
	s_nop 0
	s_nop 0
	s_nop 0
	s_nop 0
	s_nop 0
	s_nop 0
	s_nop 0
	s_nop 0
	s_nop 0
	s_nop 0
	s_nop 0
	s_nop 0
	s_nop 0
	s_nop 0
	s_nop 0
	s_nop 0
	s_nop 0
	s_nop 0
	s_nop 0
	s_nop 0
	s_nop 0
	s_nop 0
	s_nop 0
	s_nop 0
	s_nop 0
	s_nop 0
	s_nop 0
	s_nop 0
	s_nop 0
	s_nop 0
	s_nop 0
	s_nop 0
	s_nop 0
	s_nop 0
	s_nop 0
	s_nop 0
	s_nop 0
	s_nop 0
	s_nop 0
	s_nop 0
	s_nop 0
	s_nop 0
	s_nop 0
	s_nop 0
	s_nop 0
	s_nop 0
	s_nop 0
	s_nop 0
	s_nop 0
	s_nop 0
	s_nop 0
	s_nop 0
	s_nop 0
	s_nop 0
	s_nop 0
	s_nop 0
	s_nop 0
	s_nop 0
	s_nop 0
	s_nop 0
	s_nop 0
	s_nop 0
	s_nop 0
	s_nop 0
	s_nop 0
	s_nop 0
	s_nop 0
	s_nop 0
	s_nop 0
	s_nop 0
	s_nop 0
	s_nop 0
	s_nop 0
	s_nop 0
	s_nop 0
	s_nop 0
	s_nop 0
	s_nop 0
	s_nop 0
	s_nop 0
	s_nop 0
	s_nop 0
	s_nop 0
	s_nop 0
	s_nop 0
	s_nop 0
	s_nop 0
	s_nop 0
	s_nop 0
	s_nop 0
	s_nop 0
	s_nop 0
	s_nop 0
	s_nop 0
	s_nop 0
	s_nop 0
	s_nop 0
	s_nop 0
	s_nop 0
	s_nop 0
	s_nop 0
	s_nop 0
	s_nop 0
	s_nop 0
	s_nop 0
	s_nop 0
	s_nop 0
	s_nop 0
	s_nop 0
	s_nop 0
	s_nop 0
	s_nop 0
	s_nop 0
	s_nop 0
	s_nop 0
	s_nop 0
	s_nop 0
	s_nop 0
	s_nop 0
	s_nop 0
	s_nop 0
	s_nop 0
	s_nop 0
	s_nop 0
	s_nop 0
	s_nop 0
	s_nop 0
	s_nop 0
	s_nop 0
	s_nop 0
	s_nop 0
	s_nop 0
	s_nop 0
	s_nop 0
	s_nop 0
	s_nop 0
	s_nop 0
	s_nop 0
	s_nop 0
	s_nop 0
	s_nop 0
	s_nop 0
	s_nop 0
	s_nop 0
	s_nop 0
	s_nop 0
	s_nop 0
	s_nop 0
	s_nop 0
	s_nop 0
	s_nop 0
	s_nop 0
	s_nop 0
	s_nop 0
	s_nop 0
	s_nop 0
	s_nop 0
	s_nop 0
	s_nop 0
	s_nop 0
	s_nop 0
	s_nop 0
	s_nop 0
	s_nop 0
	s_nop 0
	s_nop 0
	s_nop 0
	s_nop 0
	s_nop 0
	s_nop 0
	s_nop 0
	s_nop 0
	s_nop 0
	s_nop 0
	s_nop 0
	s_nop 0
	s_nop 0
	s_nop 0
	s_nop 0
	s_nop 0
	s_nop 0
	s_nop 0
	s_nop 0
	s_nop 0
	s_nop 0
	s_nop 0
	s_nop 0
	s_nop 0
	s_nop 0
	s_nop 0
	s_nop 0
	s_nop 0
	s_nop 0
	s_nop 0
	s_nop 0
	s_nop 0
	s_nop 0
	s_nop 0
	s_nop 0
	s_nop 0
	s_nop 0
	s_nop 0
	s_nop 0
	s_nop 0
	s_nop 0
	s_nop 0
	s_nop 0
	s_nop 0
	s_nop 0
	s_nop 0
	s_nop 0
	s_nop 0
	s_nop 0
	s_nop 0
	s_nop 0
	s_nop 0
	s_nop 0
	s_nop 0
	s_nop 0
	s_nop 0
	s_nop 0
	s_nop 0
	s_nop 0
	s_nop 0
	s_nop 0
	s_nop 0
	s_nop 0
	s_nop 0
	s_nop 0
	s_nop 0
	s_nop 0
	s_nop 0
	s_nop 0
	s_nop 0
	s_nop 0
	s_nop 0
	s_nop 0
	s_nop 0
	s_nop 0
	s_nop 0
	s_nop 0
	s_nop 0
	s_nop 0
	s_nop 0
	s_nop 0
	s_nop 0
	s_nop 0
	s_nop 0
	s_nop 0
	s_nop 0
	s_nop 0
	s_nop 0
	s_nop 0
	s_nop 0
	s_nop 0
	s_nop 0
	s_nop 0
	s_nop 0
	s_nop 0
	s_nop 0
	s_nop 0
	s_nop 0
	s_nop 0
	s_nop 0
	s_nop 0
	s_nop 0
	s_nop 0
	s_nop 0
	s_nop 0
	s_nop 0
	s_nop 0
	s_nop 0
	s_nop 0
	s_nop 0
	s_nop 0
	s_nop 0
	s_nop 0
	s_nop 0
	s_nop 0
	s_nop 0
	s_nop 0
	s_nop 0
	s_nop 0
	s_nop 0
	s_nop 0
	s_nop 0
	s_nop 0
	s_nop 0
	s_nop 0
	s_nop 0
	s_nop 0
	s_nop 0
	s_nop 0
	s_nop 0
	s_nop 0
	s_nop 0
	s_nop 0
	s_nop 0
	s_nop 0
	s_nop 0
	s_nop 0
	s_nop 0
	s_nop 0
	s_nop 0
	s_nop 0
	s_nop 0
	s_nop 0
	s_nop 0
	s_nop 0
	s_nop 0
	s_nop 0
	s_nop 0
	s_nop 0
	s_nop 0
	s_nop 0
	s_nop 0
	s_nop 0
	s_nop 0
	s_nop 0
	s_nop 0
	s_nop 0
	s_nop 0
	s_nop 0
	s_nop 0
	s_nop 0
	s_nop 0
	s_nop 0
	s_nop 0
	s_nop 0
	s_nop 0
	s_nop 0
.LBB0_750:
	s_waitcnt vmcnt(0)
	s_waitcnt lgkmcnt(0)
	s_barrier
	s_and_saveexec_b64 s[0:1], s[56:57]
	s_cbranch_execz .LBB0_802
	s_add_i32 s3, 0, 0x27fc0
	s_waitcnt vmcnt(15)
	v_mov_b32_e32 v0, s3
	s_waitcnt vmcnt(0) expcnt(0) lgkmcnt(0)
	ds_read_b32 v2, v0
	s_add_i32 s3, 0, 0x27fc4
	v_mov_b32_e32 v0, s3
	ds_read_b32 v0, v0
	s_waitcnt lgkmcnt(1)
	v_cmp_ne_u32_e32 vcc, 0, v2
	s_cbranch_vccnz .LBB0_766
	s_add_u32 s4, s28, 0x1000
	s_addc_u32 s5, s29, 0
	s_add_u32 s6, s28, 0x1100
	s_addc_u32 s7, s29, 0
	s_add_u32 s8, s28, 0x1200
	v_readlane_b32 s3, v254, 8
	s_addc_u32 s9, s29, 0
	s_mul_i32 s3, s31, s3
	s_add_u32 s10, s28, 0x1300
	s_mul_i32 s3, s3, s30
	s_addc_u32 s11, s29, 0
	s_mov_b32 s16, 1
	v_mov_b32_e32 v16, 0
	s_branch .LBB0_754
